# v56 + SchedH sigmoid fast path: -log2e multiply and +1.0 add as packed f32 on accumulator pairs (per unit 256 scalar ops -> 128 packed; same IEEE ops)
# speedup vs baseline: 1.0044x; 1.0044x over previous
.Lsh_k01:
	s_cmp_eq_u32 s63, 0
	s_cselect_b32 s5, s43, s45
	s_cselect_b32 s4, s42, s44
	v_mov_b32_e32 v156, v136
	v_add_u32_e32 v157, 0x8000, v136
	v_add_u32_e32 v158, 0x10000, v136
	v_add_u32_e32 v159, 0x18000, v136
	v_add_u32_e32 v160, 0x40000, v136
	v_add_u32_e32 v161, 0x48000, v136
	v_add_u32_e32 v162, 0x50000, v136
	v_add_u32_e32 v163, 0x58000, v136
	v_mov_b32_e32 v164, 0xbfb8aa3b
	v_pk_mul_f32 v[120:121], v[120:121], v[164:165] op_sel_hi:[1,0]
	v_pk_mul_f32 v[122:123], v[122:123], v[164:165] op_sel_hi:[1,0]
	v_pk_mul_f32 v[124:125], v[124:125], v[164:165] op_sel_hi:[1,0]
	v_pk_mul_f32 v[126:127], v[126:127], v[164:165] op_sel_hi:[1,0]
	v_exp_f32_e32 v124, v124
	v_exp_f32_e32 v120, v120
	v_exp_f32_e32 v125, v125
	v_exp_f32_e32 v121, v121
	v_exp_f32_e32 v126, v126
	v_exp_f32_e32 v122, v122
	v_exp_f32_e32 v123, v123
	v_exp_f32_e32 v127, v127
	v_pk_add_f32 v[120:121], v[120:121], 1.0 op_sel_hi:[1,0]
	v_pk_add_f32 v[122:123], v[122:123], 1.0 op_sel_hi:[1,0]
	v_pk_add_f32 v[124:125], v[124:125], 1.0 op_sel_hi:[1,0]
	v_pk_add_f32 v[126:127], v[126:127], 1.0 op_sel_hi:[1,0]
	v_rcp_f32_e32 v124, v124
	v_rcp_f32_e32 v120, v120
	v_rcp_f32_e32 v121, v121
	v_rcp_f32_e32 v126, v126
	v_rcp_f32_e32 v122, v122
	v_rcp_f32_e32 v123, v123
	v_rcp_f32_e32 v127, v127
	v_rcp_f32_e32 v125, v125
	s_nop 0
	v_cvt_pk_f16_f32 v123, v122, v123
	v_cvt_pk_f16_f32 v122, v120, v121
	v_cvt_pk_f16_f32 v121, v126, v127
	v_cvt_pk_f16_f32 v120, v124, v125
	global_store_dwordx4 v156, v[120:123], s[4:5]
	v_pk_mul_f32 v[112:113], v[112:113], v[164:165] op_sel_hi:[1,0]
	v_pk_mul_f32 v[114:115], v[114:115], v[164:165] op_sel_hi:[1,0]
	v_pk_mul_f32 v[116:117], v[116:117], v[164:165] op_sel_hi:[1,0]
	v_pk_mul_f32 v[118:119], v[118:119], v[164:165] op_sel_hi:[1,0]
	v_exp_f32_e32 v116, v116
	v_exp_f32_e32 v112, v112
	v_exp_f32_e32 v117, v117
	v_exp_f32_e32 v113, v113
	v_exp_f32_e32 v118, v118
	v_exp_f32_e32 v114, v114
	v_exp_f32_e32 v115, v115
	v_exp_f32_e32 v119, v119
	v_pk_add_f32 v[112:113], v[112:113], 1.0 op_sel_hi:[1,0]
	v_pk_add_f32 v[114:115], v[114:115], 1.0 op_sel_hi:[1,0]
	v_pk_add_f32 v[116:117], v[116:117], 1.0 op_sel_hi:[1,0]
	v_pk_add_f32 v[118:119], v[118:119], 1.0 op_sel_hi:[1,0]
	v_rcp_f32_e32 v116, v116
	v_rcp_f32_e32 v112, v112
	v_rcp_f32_e32 v113, v113
	v_rcp_f32_e32 v118, v118
	v_rcp_f32_e32 v114, v114
	v_rcp_f32_e32 v115, v115
	v_rcp_f32_e32 v119, v119
	v_rcp_f32_e32 v117, v117
	s_nop 0
	v_cvt_pk_f16_f32 v115, v114, v115
	v_cvt_pk_f16_f32 v114, v112, v113
	v_cvt_pk_f16_f32 v113, v118, v119
	v_cvt_pk_f16_f32 v112, v116, v117
	global_store_dwordx4 v156, v[112:115], s[4:5] offset:256
	v_pk_mul_f32 v[104:105], v[104:105], v[164:165] op_sel_hi:[1,0]
	v_pk_mul_f32 v[106:107], v[106:107], v[164:165] op_sel_hi:[1,0]
	v_pk_mul_f32 v[108:109], v[108:109], v[164:165] op_sel_hi:[1,0]
	v_pk_mul_f32 v[110:111], v[110:111], v[164:165] op_sel_hi:[1,0]
	v_exp_f32_e32 v108, v108
	v_exp_f32_e32 v104, v104
	v_exp_f32_e32 v109, v109
	v_exp_f32_e32 v105, v105
	v_exp_f32_e32 v110, v110
	v_exp_f32_e32 v106, v106
	v_exp_f32_e32 v107, v107
	v_exp_f32_e32 v111, v111
	v_pk_add_f32 v[104:105], v[104:105], 1.0 op_sel_hi:[1,0]
	v_pk_add_f32 v[106:107], v[106:107], 1.0 op_sel_hi:[1,0]
	v_pk_add_f32 v[108:109], v[108:109], 1.0 op_sel_hi:[1,0]
	v_pk_add_f32 v[110:111], v[110:111], 1.0 op_sel_hi:[1,0]
	v_rcp_f32_e32 v108, v108
	v_rcp_f32_e32 v104, v104
	v_rcp_f32_e32 v105, v105
	v_rcp_f32_e32 v110, v110
	v_rcp_f32_e32 v106, v106
	v_rcp_f32_e32 v107, v107
	v_rcp_f32_e32 v111, v111
	v_rcp_f32_e32 v109, v109
	s_nop 0
	v_cvt_pk_f16_f32 v107, v106, v107
	v_cvt_pk_f16_f32 v106, v104, v105
	v_cvt_pk_f16_f32 v105, v110, v111
	v_cvt_pk_f16_f32 v104, v108, v109
	global_store_dwordx4 v157, v[104:107], s[4:5]
	v_pk_mul_f32 v[96:97], v[96:97], v[164:165] op_sel_hi:[1,0]
	v_pk_mul_f32 v[98:99], v[98:99], v[164:165] op_sel_hi:[1,0]
	v_pk_mul_f32 v[100:101], v[100:101], v[164:165] op_sel_hi:[1,0]
	v_pk_mul_f32 v[102:103], v[102:103], v[164:165] op_sel_hi:[1,0]
	v_exp_f32_e32 v100, v100
	v_exp_f32_e32 v96, v96
	v_exp_f32_e32 v101, v101
	v_exp_f32_e32 v97, v97
	v_exp_f32_e32 v102, v102
	v_exp_f32_e32 v98, v98
	v_exp_f32_e32 v99, v99
	v_exp_f32_e32 v103, v103
	v_pk_add_f32 v[96:97], v[96:97], 1.0 op_sel_hi:[1,0]
	v_pk_add_f32 v[98:99], v[98:99], 1.0 op_sel_hi:[1,0]
	v_pk_add_f32 v[100:101], v[100:101], 1.0 op_sel_hi:[1,0]
	v_pk_add_f32 v[102:103], v[102:103], 1.0 op_sel_hi:[1,0]
	v_rcp_f32_e32 v100, v100
	v_rcp_f32_e32 v96, v96
	v_rcp_f32_e32 v97, v97
	v_rcp_f32_e32 v102, v102
	v_rcp_f32_e32 v98, v98
	v_rcp_f32_e32 v99, v99
	v_rcp_f32_e32 v103, v103
	v_rcp_f32_e32 v101, v101
	s_nop 0
	v_cvt_pk_f16_f32 v99, v98, v99
	v_cvt_pk_f16_f32 v98, v96, v97
	v_cvt_pk_f16_f32 v97, v102, v103
	v_cvt_pk_f16_f32 v96, v100, v101
	global_store_dwordx4 v157, v[96:99], s[4:5] offset:256
	v_pk_mul_f32 v[88:89], v[88:89], v[164:165] op_sel_hi:[1,0]
	v_pk_mul_f32 v[90:91], v[90:91], v[164:165] op_sel_hi:[1,0]
	v_pk_mul_f32 v[92:93], v[92:93], v[164:165] op_sel_hi:[1,0]
	v_pk_mul_f32 v[94:95], v[94:95], v[164:165] op_sel_hi:[1,0]
	v_exp_f32_e32 v92, v92
	v_exp_f32_e32 v88, v88
	v_exp_f32_e32 v93, v93
	v_exp_f32_e32 v89, v89
	v_exp_f32_e32 v94, v94
	v_exp_f32_e32 v90, v90
	v_exp_f32_e32 v91, v91
	v_exp_f32_e32 v95, v95
	v_pk_add_f32 v[88:89], v[88:89], 1.0 op_sel_hi:[1,0]
	v_pk_add_f32 v[90:91], v[90:91], 1.0 op_sel_hi:[1,0]
	v_pk_add_f32 v[92:93], v[92:93], 1.0 op_sel_hi:[1,0]
	v_pk_add_f32 v[94:95], v[94:95], 1.0 op_sel_hi:[1,0]
	v_rcp_f32_e32 v92, v92
	v_rcp_f32_e32 v88, v88
	v_rcp_f32_e32 v89, v89
	v_rcp_f32_e32 v94, v94
	v_rcp_f32_e32 v90, v90
	v_rcp_f32_e32 v91, v91
	v_rcp_f32_e32 v95, v95
	v_rcp_f32_e32 v93, v93
	s_nop 0
	v_cvt_pk_f16_f32 v91, v90, v91
	v_cvt_pk_f16_f32 v90, v88, v89
	v_cvt_pk_f16_f32 v89, v94, v95
	v_cvt_pk_f16_f32 v88, v92, v93
	global_store_dwordx4 v158, v[88:91], s[4:5]
	v_pk_mul_f32 v[80:81], v[80:81], v[164:165] op_sel_hi:[1,0]
	v_pk_mul_f32 v[82:83], v[82:83], v[164:165] op_sel_hi:[1,0]
	v_pk_mul_f32 v[84:85], v[84:85], v[164:165] op_sel_hi:[1,0]
	v_pk_mul_f32 v[86:87], v[86:87], v[164:165] op_sel_hi:[1,0]
	v_exp_f32_e32 v84, v84
	v_exp_f32_e32 v80, v80
	v_exp_f32_e32 v85, v85
	v_exp_f32_e32 v81, v81
	v_exp_f32_e32 v86, v86
	v_exp_f32_e32 v82, v82
	v_exp_f32_e32 v83, v83
	v_exp_f32_e32 v87, v87
	v_pk_add_f32 v[80:81], v[80:81], 1.0 op_sel_hi:[1,0]
	v_pk_add_f32 v[82:83], v[82:83], 1.0 op_sel_hi:[1,0]
	v_pk_add_f32 v[84:85], v[84:85], 1.0 op_sel_hi:[1,0]
	v_pk_add_f32 v[86:87], v[86:87], 1.0 op_sel_hi:[1,0]
	v_rcp_f32_e32 v84, v84
	v_rcp_f32_e32 v80, v80
	v_rcp_f32_e32 v81, v81
	v_rcp_f32_e32 v86, v86
	v_rcp_f32_e32 v82, v82
	v_rcp_f32_e32 v83, v83
	v_rcp_f32_e32 v87, v87
	v_rcp_f32_e32 v85, v85
	s_nop 0
	v_cvt_pk_f16_f32 v83, v82, v83
	v_cvt_pk_f16_f32 v82, v80, v81
	v_cvt_pk_f16_f32 v81, v86, v87
	v_cvt_pk_f16_f32 v80, v84, v85
	global_store_dwordx4 v158, v[80:83], s[4:5] offset:256
	v_pk_mul_f32 v[72:73], v[72:73], v[164:165] op_sel_hi:[1,0]
	v_pk_mul_f32 v[74:75], v[74:75], v[164:165] op_sel_hi:[1,0]
	v_pk_mul_f32 v[76:77], v[76:77], v[164:165] op_sel_hi:[1,0]
	v_pk_mul_f32 v[78:79], v[78:79], v[164:165] op_sel_hi:[1,0]
	v_exp_f32_e32 v76, v76
	v_exp_f32_e32 v72, v72
	v_exp_f32_e32 v77, v77
	v_exp_f32_e32 v73, v73
	v_exp_f32_e32 v78, v78
	v_exp_f32_e32 v74, v74
	v_exp_f32_e32 v75, v75
	v_exp_f32_e32 v79, v79
	v_pk_add_f32 v[72:73], v[72:73], 1.0 op_sel_hi:[1,0]
	v_pk_add_f32 v[74:75], v[74:75], 1.0 op_sel_hi:[1,0]
	v_pk_add_f32 v[76:77], v[76:77], 1.0 op_sel_hi:[1,0]
	v_pk_add_f32 v[78:79], v[78:79], 1.0 op_sel_hi:[1,0]
	v_rcp_f32_e32 v76, v76
	v_rcp_f32_e32 v72, v72
	v_rcp_f32_e32 v73, v73
	v_rcp_f32_e32 v78, v78
	v_rcp_f32_e32 v74, v74
	v_rcp_f32_e32 v75, v75
	v_rcp_f32_e32 v79, v79
	v_rcp_f32_e32 v77, v77
	s_nop 0
	v_cvt_pk_f16_f32 v75, v74, v75
	v_cvt_pk_f16_f32 v74, v72, v73
	v_cvt_pk_f16_f32 v73, v78, v79
	v_cvt_pk_f16_f32 v72, v76, v77
	global_store_dwordx4 v159, v[72:75], s[4:5]
	v_pk_mul_f32 v[64:65], v[64:65], v[164:165] op_sel_hi:[1,0]
	v_pk_mul_f32 v[66:67], v[66:67], v[164:165] op_sel_hi:[1,0]
	v_pk_mul_f32 v[68:69], v[68:69], v[164:165] op_sel_hi:[1,0]
	v_pk_mul_f32 v[70:71], v[70:71], v[164:165] op_sel_hi:[1,0]
	v_exp_f32_e32 v68, v68
	v_exp_f32_e32 v64, v64
	v_exp_f32_e32 v69, v69
	v_exp_f32_e32 v65, v65
	v_exp_f32_e32 v70, v70
	v_exp_f32_e32 v66, v66
	v_exp_f32_e32 v67, v67
	v_exp_f32_e32 v71, v71
	v_pk_add_f32 v[64:65], v[64:65], 1.0 op_sel_hi:[1,0]
	v_pk_add_f32 v[66:67], v[66:67], 1.0 op_sel_hi:[1,0]
	v_pk_add_f32 v[68:69], v[68:69], 1.0 op_sel_hi:[1,0]
	v_pk_add_f32 v[70:71], v[70:71], 1.0 op_sel_hi:[1,0]
	v_rcp_f32_e32 v68, v68
	v_rcp_f32_e32 v64, v64
	v_rcp_f32_e32 v65, v65
	v_rcp_f32_e32 v70, v70
	v_rcp_f32_e32 v66, v66
	v_rcp_f32_e32 v67, v67
	v_rcp_f32_e32 v71, v71
	v_rcp_f32_e32 v69, v69
	s_nop 0
	v_cvt_pk_f16_f32 v67, v66, v67
	v_cvt_pk_f16_f32 v66, v64, v65
	v_cvt_pk_f16_f32 v65, v70, v71
	v_cvt_pk_f16_f32 v64, v68, v69
	global_store_dwordx4 v159, v[64:67], s[4:5] offset:256
	v_pk_mul_f32 v[56:57], v[56:57], v[164:165] op_sel_hi:[1,0]
	v_pk_mul_f32 v[58:59], v[58:59], v[164:165] op_sel_hi:[1,0]
	v_pk_mul_f32 v[60:61], v[60:61], v[164:165] op_sel_hi:[1,0]
	v_pk_mul_f32 v[62:63], v[62:63], v[164:165] op_sel_hi:[1,0]
	v_exp_f32_e32 v60, v60
	v_exp_f32_e32 v56, v56
	v_exp_f32_e32 v61, v61
	v_exp_f32_e32 v57, v57
	v_exp_f32_e32 v62, v62
	v_exp_f32_e32 v58, v58
	v_exp_f32_e32 v59, v59
	v_exp_f32_e32 v63, v63
	v_pk_add_f32 v[56:57], v[56:57], 1.0 op_sel_hi:[1,0]
	v_pk_add_f32 v[58:59], v[58:59], 1.0 op_sel_hi:[1,0]
	v_pk_add_f32 v[60:61], v[60:61], 1.0 op_sel_hi:[1,0]
	v_pk_add_f32 v[62:63], v[62:63], 1.0 op_sel_hi:[1,0]
	v_rcp_f32_e32 v60, v60
	v_rcp_f32_e32 v56, v56
	v_rcp_f32_e32 v57, v57
	v_rcp_f32_e32 v62, v62
	v_rcp_f32_e32 v58, v58
	v_rcp_f32_e32 v59, v59
	v_rcp_f32_e32 v63, v63
	v_rcp_f32_e32 v61, v61
	s_nop 0
	v_cvt_pk_f16_f32 v59, v58, v59
	v_cvt_pk_f16_f32 v58, v56, v57
	v_cvt_pk_f16_f32 v57, v62, v63
	v_cvt_pk_f16_f32 v56, v60, v61
	global_store_dwordx4 v160, v[56:59], s[4:5]
	v_pk_mul_f32 v[48:49], v[48:49], v[164:165] op_sel_hi:[1,0]
	v_pk_mul_f32 v[50:51], v[50:51], v[164:165] op_sel_hi:[1,0]
	v_pk_mul_f32 v[52:53], v[52:53], v[164:165] op_sel_hi:[1,0]
	v_pk_mul_f32 v[54:55], v[54:55], v[164:165] op_sel_hi:[1,0]
	v_exp_f32_e32 v52, v52
	v_exp_f32_e32 v48, v48
	v_exp_f32_e32 v53, v53
	v_exp_f32_e32 v49, v49
	v_exp_f32_e32 v54, v54
	v_exp_f32_e32 v50, v50
	v_exp_f32_e32 v51, v51
	v_exp_f32_e32 v55, v55
	v_pk_add_f32 v[48:49], v[48:49], 1.0 op_sel_hi:[1,0]
	v_pk_add_f32 v[50:51], v[50:51], 1.0 op_sel_hi:[1,0]
	v_pk_add_f32 v[52:53], v[52:53], 1.0 op_sel_hi:[1,0]
	v_pk_add_f32 v[54:55], v[54:55], 1.0 op_sel_hi:[1,0]
	v_rcp_f32_e32 v52, v52
	v_rcp_f32_e32 v48, v48
	v_rcp_f32_e32 v49, v49
	v_rcp_f32_e32 v54, v54
	v_rcp_f32_e32 v50, v50
	v_rcp_f32_e32 v51, v51
	v_rcp_f32_e32 v55, v55
	v_rcp_f32_e32 v53, v53
	s_nop 0
	v_cvt_pk_f16_f32 v51, v50, v51
	v_cvt_pk_f16_f32 v50, v48, v49
	v_cvt_pk_f16_f32 v49, v54, v55
	v_cvt_pk_f16_f32 v48, v52, v53
	global_store_dwordx4 v160, v[48:51], s[4:5] offset:256
	v_pk_mul_f32 v[40:41], v[40:41], v[164:165] op_sel_hi:[1,0]
	v_pk_mul_f32 v[42:43], v[42:43], v[164:165] op_sel_hi:[1,0]
	v_pk_mul_f32 v[44:45], v[44:45], v[164:165] op_sel_hi:[1,0]
	v_pk_mul_f32 v[46:47], v[46:47], v[164:165] op_sel_hi:[1,0]
	v_exp_f32_e32 v44, v44
	v_exp_f32_e32 v40, v40
	v_exp_f32_e32 v45, v45
	v_exp_f32_e32 v41, v41
	v_exp_f32_e32 v46, v46
	v_exp_f32_e32 v42, v42
	v_exp_f32_e32 v43, v43
	v_exp_f32_e32 v47, v47
	v_pk_add_f32 v[40:41], v[40:41], 1.0 op_sel_hi:[1,0]
	v_pk_add_f32 v[42:43], v[42:43], 1.0 op_sel_hi:[1,0]
	v_pk_add_f32 v[44:45], v[44:45], 1.0 op_sel_hi:[1,0]
	v_pk_add_f32 v[46:47], v[46:47], 1.0 op_sel_hi:[1,0]
	v_rcp_f32_e32 v44, v44
	v_rcp_f32_e32 v40, v40
	v_rcp_f32_e32 v41, v41
	v_rcp_f32_e32 v46, v46
	v_rcp_f32_e32 v42, v42
	v_rcp_f32_e32 v43, v43
	v_rcp_f32_e32 v47, v47
	v_rcp_f32_e32 v45, v45
	s_nop 0
	v_cvt_pk_f16_f32 v43, v42, v43
	v_cvt_pk_f16_f32 v42, v40, v41
	v_cvt_pk_f16_f32 v41, v46, v47
	v_cvt_pk_f16_f32 v40, v44, v45
	global_store_dwordx4 v161, v[40:43], s[4:5]
	v_pk_mul_f32 v[32:33], v[32:33], v[164:165] op_sel_hi:[1,0]
	v_pk_mul_f32 v[34:35], v[34:35], v[164:165] op_sel_hi:[1,0]
	v_pk_mul_f32 v[36:37], v[36:37], v[164:165] op_sel_hi:[1,0]
	v_pk_mul_f32 v[38:39], v[38:39], v[164:165] op_sel_hi:[1,0]
	v_exp_f32_e32 v36, v36
	v_exp_f32_e32 v32, v32
	v_exp_f32_e32 v37, v37
	v_exp_f32_e32 v33, v33
	v_exp_f32_e32 v38, v38
	v_exp_f32_e32 v34, v34
	v_exp_f32_e32 v35, v35
	v_exp_f32_e32 v39, v39
	v_pk_add_f32 v[32:33], v[32:33], 1.0 op_sel_hi:[1,0]
	v_pk_add_f32 v[34:35], v[34:35], 1.0 op_sel_hi:[1,0]
	v_pk_add_f32 v[36:37], v[36:37], 1.0 op_sel_hi:[1,0]
	v_pk_add_f32 v[38:39], v[38:39], 1.0 op_sel_hi:[1,0]
	v_rcp_f32_e32 v36, v36
	v_rcp_f32_e32 v32, v32
	v_rcp_f32_e32 v33, v33
	v_rcp_f32_e32 v38, v38
	v_rcp_f32_e32 v34, v34
	v_rcp_f32_e32 v35, v35
	v_rcp_f32_e32 v39, v39
	v_rcp_f32_e32 v37, v37
	s_nop 0
	v_cvt_pk_f16_f32 v35, v34, v35
	v_cvt_pk_f16_f32 v34, v32, v33
	v_cvt_pk_f16_f32 v33, v38, v39
	v_cvt_pk_f16_f32 v32, v36, v37
	global_store_dwordx4 v161, v[32:35], s[4:5] offset:256
	v_pk_mul_f32 v[24:25], v[24:25], v[164:165] op_sel_hi:[1,0]
	v_pk_mul_f32 v[26:27], v[26:27], v[164:165] op_sel_hi:[1,0]
	v_pk_mul_f32 v[28:29], v[28:29], v[164:165] op_sel_hi:[1,0]
	v_pk_mul_f32 v[30:31], v[30:31], v[164:165] op_sel_hi:[1,0]
	v_exp_f32_e32 v28, v28
	v_exp_f32_e32 v24, v24
	v_exp_f32_e32 v29, v29
	v_exp_f32_e32 v25, v25
	v_exp_f32_e32 v30, v30
	v_exp_f32_e32 v26, v26
	v_exp_f32_e32 v27, v27
	v_exp_f32_e32 v31, v31
	v_pk_add_f32 v[24:25], v[24:25], 1.0 op_sel_hi:[1,0]
	v_pk_add_f32 v[26:27], v[26:27], 1.0 op_sel_hi:[1,0]
	v_pk_add_f32 v[28:29], v[28:29], 1.0 op_sel_hi:[1,0]
	v_pk_add_f32 v[30:31], v[30:31], 1.0 op_sel_hi:[1,0]
	v_rcp_f32_e32 v28, v28
	v_rcp_f32_e32 v24, v24
	v_rcp_f32_e32 v25, v25
	v_rcp_f32_e32 v30, v30
	v_rcp_f32_e32 v26, v26
	v_rcp_f32_e32 v27, v27
	v_rcp_f32_e32 v31, v31
	v_rcp_f32_e32 v29, v29
	s_nop 0
	v_cvt_pk_f16_f32 v27, v26, v27
	v_cvt_pk_f16_f32 v26, v24, v25
	v_cvt_pk_f16_f32 v25, v30, v31
	v_cvt_pk_f16_f32 v24, v28, v29
	global_store_dwordx4 v162, v[24:27], s[4:5]
	v_pk_mul_f32 v[16:17], v[16:17], v[164:165] op_sel_hi:[1,0]
	v_pk_mul_f32 v[18:19], v[18:19], v[164:165] op_sel_hi:[1,0]
	v_pk_mul_f32 v[20:21], v[20:21], v[164:165] op_sel_hi:[1,0]
	v_pk_mul_f32 v[22:23], v[22:23], v[164:165] op_sel_hi:[1,0]
	v_exp_f32_e32 v20, v20
	v_exp_f32_e32 v16, v16
	v_exp_f32_e32 v21, v21
	v_exp_f32_e32 v17, v17
	v_exp_f32_e32 v22, v22
	v_exp_f32_e32 v18, v18
	v_exp_f32_e32 v19, v19
	v_exp_f32_e32 v23, v23
	v_pk_add_f32 v[16:17], v[16:17], 1.0 op_sel_hi:[1,0]
	v_pk_add_f32 v[18:19], v[18:19], 1.0 op_sel_hi:[1,0]
	v_pk_add_f32 v[20:21], v[20:21], 1.0 op_sel_hi:[1,0]
	v_pk_add_f32 v[22:23], v[22:23], 1.0 op_sel_hi:[1,0]
	v_rcp_f32_e32 v20, v20
	v_rcp_f32_e32 v16, v16
	v_rcp_f32_e32 v17, v17
	v_rcp_f32_e32 v22, v22
	v_rcp_f32_e32 v18, v18
	v_rcp_f32_e32 v19, v19
	v_rcp_f32_e32 v23, v23
	v_rcp_f32_e32 v21, v21
	s_nop 0
	v_cvt_pk_f16_f32 v19, v18, v19
	v_cvt_pk_f16_f32 v18, v16, v17
	v_cvt_pk_f16_f32 v17, v22, v23
	v_cvt_pk_f16_f32 v16, v20, v21
	global_store_dwordx4 v162, v[16:19], s[4:5] offset:256
	v_pk_mul_f32 v[8:9], v[8:9], v[164:165] op_sel_hi:[1,0]
	v_pk_mul_f32 v[10:11], v[10:11], v[164:165] op_sel_hi:[1,0]
	v_pk_mul_f32 v[12:13], v[12:13], v[164:165] op_sel_hi:[1,0]
	v_pk_mul_f32 v[14:15], v[14:15], v[164:165] op_sel_hi:[1,0]
	v_exp_f32_e32 v12, v12
	v_exp_f32_e32 v8, v8
	v_exp_f32_e32 v13, v13
	v_exp_f32_e32 v9, v9
	v_exp_f32_e32 v14, v14
	v_exp_f32_e32 v10, v10
	v_exp_f32_e32 v11, v11
	v_exp_f32_e32 v15, v15
	v_pk_add_f32 v[8:9], v[8:9], 1.0 op_sel_hi:[1,0]
	v_pk_add_f32 v[10:11], v[10:11], 1.0 op_sel_hi:[1,0]
	v_pk_add_f32 v[12:13], v[12:13], 1.0 op_sel_hi:[1,0]
	v_pk_add_f32 v[14:15], v[14:15], 1.0 op_sel_hi:[1,0]
	v_rcp_f32_e32 v12, v12
	v_rcp_f32_e32 v8, v8
	v_rcp_f32_e32 v9, v9
	v_rcp_f32_e32 v14, v14
	v_rcp_f32_e32 v10, v10
	v_rcp_f32_e32 v11, v11
	v_rcp_f32_e32 v15, v15
	v_rcp_f32_e32 v13, v13
	s_nop 0
	v_cvt_pk_f16_f32 v11, v10, v11
	v_cvt_pk_f16_f32 v10, v8, v9
	v_cvt_pk_f16_f32 v9, v14, v15
	v_cvt_pk_f16_f32 v8, v12, v13
	global_store_dwordx4 v163, v[8:11], s[4:5]
	v_pk_mul_f32 v[0:1], v[0:1], v[164:165] op_sel_hi:[1,0]
	v_pk_mul_f32 v[2:3], v[2:3], v[164:165] op_sel_hi:[1,0]
	v_pk_mul_f32 v[4:5], v[4:5], v[164:165] op_sel_hi:[1,0]
	v_pk_mul_f32 v[6:7], v[6:7], v[164:165] op_sel_hi:[1,0]
	v_exp_f32_e32 v4, v4
	v_exp_f32_e32 v0, v0
	v_exp_f32_e32 v5, v5
	v_exp_f32_e32 v1, v1
	v_exp_f32_e32 v6, v6
	v_exp_f32_e32 v2, v2
	v_exp_f32_e32 v3, v3
	v_exp_f32_e32 v7, v7
	v_pk_add_f32 v[0:1], v[0:1], 1.0 op_sel_hi:[1,0]
	v_pk_add_f32 v[2:3], v[2:3], 1.0 op_sel_hi:[1,0]
	v_pk_add_f32 v[4:5], v[4:5], 1.0 op_sel_hi:[1,0]
	v_pk_add_f32 v[6:7], v[6:7], 1.0 op_sel_hi:[1,0]
	v_rcp_f32_e32 v4, v4
	v_rcp_f32_e32 v0, v0
	v_rcp_f32_e32 v1, v1
	v_rcp_f32_e32 v6, v6
	v_rcp_f32_e32 v2, v2
	v_rcp_f32_e32 v3, v3
	v_rcp_f32_e32 v7, v7
	v_rcp_f32_e32 v5, v5
	s_nop 0
	v_cvt_pk_f16_f32 v3, v2, v3
	v_cvt_pk_f16_f32 v2, v0, v1
	v_cvt_pk_f16_f32 v1, v6, v7
	v_cvt_pk_f16_f32 v0, v4, v5
	global_store_dwordx4 v163, v[0:3], s[4:5] offset:256
	s_branch .LBB0_1145
